# prep tail (CW = Cc W, SW = Sc W) with its weight loads three batches ahead instead of 16 serialized round trips: half the workgroups ran it for 13.5 us between the arrival at the first grid barrier an
# baseline (speedup 1.0000x reference)
.LBB0_72:
	v_lshlrev_b32_e32 v59, 2, v3
	v_mov_b32_e32 v9, 0
	global_load_dword v60, v[10:11], off offset:-512
	global_load_dword v61, v[10:11], off
	global_load_dword v62, v[10:11], off offset:512
	global_load_dword v63, v[10:11], off offset:1024
	global_load_dword v64, v[10:11], off offset:1536
	global_load_dword v65, v[10:11], off offset:2048
	global_load_dword v66, v[10:11], off offset:2560
	global_load_dword v67, v[10:11], off offset:3072
	v_lshl_add_u64 v[10:11], v[10:11], 0, s[12:13]
	global_load_dword v68, v[10:11], off offset:-512
	global_load_dword v69, v[10:11], off
	global_load_dword v70, v[10:11], off offset:512
	global_load_dword v71, v[10:11], off offset:1024
	global_load_dword v72, v[10:11], off offset:1536
	global_load_dword v73, v[10:11], off offset:2048
	global_load_dword v74, v[10:11], off offset:2560
	global_load_dword v75, v[10:11], off offset:3072
	v_lshl_add_u64 v[10:11], v[10:11], 0, s[12:13]
	global_load_dword v76, v[10:11], off offset:-512
	global_load_dword v77, v[10:11], off
	global_load_dword v78, v[10:11], off offset:512
	global_load_dword v79, v[10:11], off offset:1024
	global_load_dword v80, v[10:11], off offset:1536
	global_load_dword v81, v[10:11], off offset:2048
	global_load_dword v82, v[10:11], off offset:2560
	global_load_dword v83, v[10:11], off offset:3072
	v_lshl_add_u64 v[10:11], v[10:11], 0, s[12:13]
	global_load_dword v84, v[10:11], off offset:-512
	global_load_dword v85, v[10:11], off
	global_load_dword v86, v[10:11], off offset:512
	global_load_dword v87, v[10:11], off offset:1024
	global_load_dword v88, v[10:11], off offset:1536
	global_load_dword v89, v[10:11], off offset:2048
	global_load_dword v90, v[10:11], off offset:2560
	global_load_dword v91, v[10:11], off offset:3072
	v_lshl_add_u64 v[10:11], v[10:11], 0, s[12:13]
	global_load_dword v92, v[10:11], off offset:-512
	global_load_dword v93, v[10:11], off
	global_load_dword v94, v[10:11], off offset:512
	global_load_dword v95, v[10:11], off offset:1024
	global_load_dword v96, v[10:11], off offset:1536
	global_load_dword v97, v[10:11], off offset:2048
	global_load_dword v98, v[10:11], off offset:2560
	global_load_dword v99, v[10:11], off offset:3072
	v_lshl_add_u64 v[10:11], v[10:11], 0, s[12:13]
	global_load_dword v100, v[10:11], off offset:-512
	global_load_dword v101, v[10:11], off
	global_load_dword v102, v[10:11], off offset:512
	global_load_dword v103, v[10:11], off offset:1024
	global_load_dword v104, v[10:11], off offset:1536
	global_load_dword v105, v[10:11], off offset:2048
	global_load_dword v106, v[10:11], off offset:2560
	global_load_dword v107, v[10:11], off offset:3072
	v_lshl_add_u64 v[10:11], v[10:11], 0, s[12:13]
	ds_read2st64_b32 v[108:109], v9 offset1:2
	v_add_u32_e32 v9, v9, v59
	v_and_b32_e32 v9, 0x1fc, v9
	ds_read2st64_b32 v[110:111], v9 offset1:2
	v_add_u32_e32 v9, v9, v59
	v_and_b32_e32 v9, 0x1fc, v9
	ds_read2st64_b32 v[112:113], v9 offset1:2
	v_add_u32_e32 v9, v9, v59
	v_and_b32_e32 v9, 0x1fc, v9
	ds_read2st64_b32 v[114:115], v9 offset1:2
	v_add_u32_e32 v9, v9, v59
	v_and_b32_e32 v9, 0x1fc, v9
	ds_read2st64_b32 v[116:117], v9 offset1:2
	v_add_u32_e32 v9, v9, v59
	v_and_b32_e32 v9, 0x1fc, v9
	ds_read2st64_b32 v[118:119], v9 offset1:2
	v_add_u32_e32 v9, v9, v59
	v_and_b32_e32 v9, 0x1fc, v9
	ds_read2st64_b32 v[120:121], v9 offset1:2
	v_add_u32_e32 v9, v9, v59
	v_and_b32_e32 v9, 0x1fc, v9
	ds_read2st64_b32 v[122:123], v9 offset1:2
	v_add_u32_e32 v9, v9, v59
	v_and_b32_e32 v9, 0x1fc, v9
	ds_read2st64_b32 v[124:125], v9 offset1:2
	v_add_u32_e32 v9, v9, v59
	v_and_b32_e32 v9, 0x1fc, v9
	ds_read2st64_b32 v[126:127], v9 offset1:2
	v_add_u32_e32 v9, v9, v59
	v_and_b32_e32 v9, 0x1fc, v9
	ds_read2st64_b32 v[128:129], v9 offset1:2
	v_add_u32_e32 v9, v9, v59
	v_and_b32_e32 v9, 0x1fc, v9
	ds_read2st64_b32 v[130:131], v9 offset1:2
	v_add_u32_e32 v9, v9, v59
	v_and_b32_e32 v9, 0x1fc, v9
	ds_read2st64_b32 v[132:133], v9 offset1:2
	v_add_u32_e32 v9, v9, v59
	v_and_b32_e32 v9, 0x1fc, v9
	ds_read2st64_b32 v[134:135], v9 offset1:2
	v_add_u32_e32 v9, v9, v59
	v_and_b32_e32 v9, 0x1fc, v9
	ds_read2st64_b32 v[136:137], v9 offset1:2
	v_add_u32_e32 v9, v9, v59
	v_and_b32_e32 v9, 0x1fc, v9
	ds_read2st64_b32 v[138:139], v9 offset1:2
	v_add_u32_e32 v9, v9, v59
	v_and_b32_e32 v9, 0x1fc, v9
	s_waitcnt lgkmcnt(8)
	s_waitcnt vmcnt(32)
	v_fmac_f32_e32 v6, v60, v109
	v_fmac_f32_e32 v7, v60, v108
	v_fmac_f32_e32 v6, v61, v111
	v_fmac_f32_e32 v7, v61, v110
	v_fmac_f32_e32 v6, v62, v113
	v_fmac_f32_e32 v7, v62, v112
	v_fmac_f32_e32 v6, v63, v115
	v_fmac_f32_e32 v7, v63, v114
	v_fmac_f32_e32 v6, v64, v117
	v_fmac_f32_e32 v7, v64, v116
	v_fmac_f32_e32 v6, v65, v119
	v_fmac_f32_e32 v7, v65, v118
	v_fmac_f32_e32 v6, v66, v121
	v_fmac_f32_e32 v7, v66, v120
	v_fmac_f32_e32 v6, v67, v123
	v_fmac_f32_e32 v7, v67, v122
	ds_read2st64_b32 v[108:109], v9 offset1:2
	v_add_u32_e32 v9, v9, v59
	v_and_b32_e32 v9, 0x1fc, v9
	ds_read2st64_b32 v[110:111], v9 offset1:2
	v_add_u32_e32 v9, v9, v59
	v_and_b32_e32 v9, 0x1fc, v9
	ds_read2st64_b32 v[112:113], v9 offset1:2
	v_add_u32_e32 v9, v9, v59
	v_and_b32_e32 v9, 0x1fc, v9
	ds_read2st64_b32 v[114:115], v9 offset1:2
	v_add_u32_e32 v9, v9, v59
	v_and_b32_e32 v9, 0x1fc, v9
	ds_read2st64_b32 v[116:117], v9 offset1:2
	v_add_u32_e32 v9, v9, v59
	v_and_b32_e32 v9, 0x1fc, v9
	ds_read2st64_b32 v[118:119], v9 offset1:2
	v_add_u32_e32 v9, v9, v59
	v_and_b32_e32 v9, 0x1fc, v9
	ds_read2st64_b32 v[120:121], v9 offset1:2
	v_add_u32_e32 v9, v9, v59
	v_and_b32_e32 v9, 0x1fc, v9
	ds_read2st64_b32 v[122:123], v9 offset1:2
	v_add_u32_e32 v9, v9, v59
	v_and_b32_e32 v9, 0x1fc, v9
	s_waitcnt lgkmcnt(8)
	v_fmac_f32_e32 v6, v68, v125
	v_fmac_f32_e32 v7, v68, v124
	v_fmac_f32_e32 v6, v69, v127
	v_fmac_f32_e32 v7, v69, v126
	v_fmac_f32_e32 v6, v70, v129
	v_fmac_f32_e32 v7, v70, v128
	v_fmac_f32_e32 v6, v71, v131
	v_fmac_f32_e32 v7, v71, v130
	v_fmac_f32_e32 v6, v72, v133
	v_fmac_f32_e32 v7, v72, v132
	v_fmac_f32_e32 v6, v73, v135
	v_fmac_f32_e32 v7, v73, v134
	v_fmac_f32_e32 v6, v74, v137
	v_fmac_f32_e32 v7, v74, v136
	v_fmac_f32_e32 v6, v75, v139
	v_fmac_f32_e32 v7, v75, v138
	global_load_dword v60, v[10:11], off offset:-512
	global_load_dword v61, v[10:11], off
	global_load_dword v62, v[10:11], off offset:512
	global_load_dword v63, v[10:11], off offset:1024
	global_load_dword v64, v[10:11], off offset:1536
	global_load_dword v65, v[10:11], off offset:2048
	global_load_dword v66, v[10:11], off offset:2560
	global_load_dword v67, v[10:11], off offset:3072
	v_lshl_add_u64 v[10:11], v[10:11], 0, s[12:13]
	global_load_dword v68, v[10:11], off offset:-512
	global_load_dword v69, v[10:11], off
	global_load_dword v70, v[10:11], off offset:512
	global_load_dword v71, v[10:11], off offset:1024
	global_load_dword v72, v[10:11], off offset:1536
	global_load_dword v73, v[10:11], off offset:2048
	global_load_dword v74, v[10:11], off offset:2560
	global_load_dword v75, v[10:11], off offset:3072
	v_lshl_add_u64 v[10:11], v[10:11], 0, s[12:13]
	ds_read2st64_b32 v[124:125], v9 offset1:2
	v_add_u32_e32 v9, v9, v59
	v_and_b32_e32 v9, 0x1fc, v9
	ds_read2st64_b32 v[126:127], v9 offset1:2
	v_add_u32_e32 v9, v9, v59
	v_and_b32_e32 v9, 0x1fc, v9
	ds_read2st64_b32 v[128:129], v9 offset1:2
	v_add_u32_e32 v9, v9, v59
	v_and_b32_e32 v9, 0x1fc, v9
	ds_read2st64_b32 v[130:131], v9 offset1:2
	v_add_u32_e32 v9, v9, v59
	v_and_b32_e32 v9, 0x1fc, v9
	ds_read2st64_b32 v[132:133], v9 offset1:2
	v_add_u32_e32 v9, v9, v59
	v_and_b32_e32 v9, 0x1fc, v9
	ds_read2st64_b32 v[134:135], v9 offset1:2
	v_add_u32_e32 v9, v9, v59
	v_and_b32_e32 v9, 0x1fc, v9
	ds_read2st64_b32 v[136:137], v9 offset1:2
	v_add_u32_e32 v9, v9, v59
	v_and_b32_e32 v9, 0x1fc, v9
	ds_read2st64_b32 v[138:139], v9 offset1:2
	v_add_u32_e32 v9, v9, v59
	v_and_b32_e32 v9, 0x1fc, v9
	s_waitcnt lgkmcnt(8)
	s_waitcnt vmcnt(32)
	v_fmac_f32_e32 v6, v76, v109
	v_fmac_f32_e32 v7, v76, v108
	v_fmac_f32_e32 v6, v77, v111
	v_fmac_f32_e32 v7, v77, v110
	v_fmac_f32_e32 v6, v78, v113
	v_fmac_f32_e32 v7, v78, v112
	v_fmac_f32_e32 v6, v79, v115
	v_fmac_f32_e32 v7, v79, v114
	v_fmac_f32_e32 v6, v80, v117
	v_fmac_f32_e32 v7, v80, v116
	v_fmac_f32_e32 v6, v81, v119
	v_fmac_f32_e32 v7, v81, v118
	v_fmac_f32_e32 v6, v82, v121
	v_fmac_f32_e32 v7, v82, v120
	v_fmac_f32_e32 v6, v83, v123
	v_fmac_f32_e32 v7, v83, v122
	ds_read2st64_b32 v[108:109], v9 offset1:2
	v_add_u32_e32 v9, v9, v59
	v_and_b32_e32 v9, 0x1fc, v9
	ds_read2st64_b32 v[110:111], v9 offset1:2
	v_add_u32_e32 v9, v9, v59
	v_and_b32_e32 v9, 0x1fc, v9
	ds_read2st64_b32 v[112:113], v9 offset1:2
	v_add_u32_e32 v9, v9, v59
	v_and_b32_e32 v9, 0x1fc, v9
	ds_read2st64_b32 v[114:115], v9 offset1:2
	v_add_u32_e32 v9, v9, v59
	v_and_b32_e32 v9, 0x1fc, v9
	ds_read2st64_b32 v[116:117], v9 offset1:2
	v_add_u32_e32 v9, v9, v59
	v_and_b32_e32 v9, 0x1fc, v9
	ds_read2st64_b32 v[118:119], v9 offset1:2
	v_add_u32_e32 v9, v9, v59
	v_and_b32_e32 v9, 0x1fc, v9
	ds_read2st64_b32 v[120:121], v9 offset1:2
	v_add_u32_e32 v9, v9, v59
	v_and_b32_e32 v9, 0x1fc, v9
	ds_read2st64_b32 v[122:123], v9 offset1:2
	v_add_u32_e32 v9, v9, v59
	v_and_b32_e32 v9, 0x1fc, v9
	s_waitcnt lgkmcnt(8)
	v_fmac_f32_e32 v6, v84, v125
	v_fmac_f32_e32 v7, v84, v124
	v_fmac_f32_e32 v6, v85, v127
	v_fmac_f32_e32 v7, v85, v126
	v_fmac_f32_e32 v6, v86, v129
	v_fmac_f32_e32 v7, v86, v128
	v_fmac_f32_e32 v6, v87, v131
	v_fmac_f32_e32 v7, v87, v130
	v_fmac_f32_e32 v6, v88, v133
	v_fmac_f32_e32 v7, v88, v132
	v_fmac_f32_e32 v6, v89, v135
	v_fmac_f32_e32 v7, v89, v134
	v_fmac_f32_e32 v6, v90, v137
	v_fmac_f32_e32 v7, v90, v136
	v_fmac_f32_e32 v6, v91, v139
	v_fmac_f32_e32 v7, v91, v138
	global_load_dword v76, v[10:11], off offset:-512
	global_load_dword v77, v[10:11], off
	global_load_dword v78, v[10:11], off offset:512
	global_load_dword v79, v[10:11], off offset:1024
	global_load_dword v80, v[10:11], off offset:1536
	global_load_dword v81, v[10:11], off offset:2048
	global_load_dword v82, v[10:11], off offset:2560
	global_load_dword v83, v[10:11], off offset:3072
	v_lshl_add_u64 v[10:11], v[10:11], 0, s[12:13]
	global_load_dword v84, v[10:11], off offset:-512
	global_load_dword v85, v[10:11], off
	global_load_dword v86, v[10:11], off offset:512
	global_load_dword v87, v[10:11], off offset:1024
	global_load_dword v88, v[10:11], off offset:1536
	global_load_dword v89, v[10:11], off offset:2048
	global_load_dword v90, v[10:11], off offset:2560
	global_load_dword v91, v[10:11], off offset:3072
	v_lshl_add_u64 v[10:11], v[10:11], 0, s[12:13]
	ds_read2st64_b32 v[124:125], v9 offset1:2
	v_add_u32_e32 v9, v9, v59
	v_and_b32_e32 v9, 0x1fc, v9
	ds_read2st64_b32 v[126:127], v9 offset1:2
	v_add_u32_e32 v9, v9, v59
	v_and_b32_e32 v9, 0x1fc, v9
	ds_read2st64_b32 v[128:129], v9 offset1:2
	v_add_u32_e32 v9, v9, v59
	v_and_b32_e32 v9, 0x1fc, v9
	ds_read2st64_b32 v[130:131], v9 offset1:2
	v_add_u32_e32 v9, v9, v59
	v_and_b32_e32 v9, 0x1fc, v9
	ds_read2st64_b32 v[132:133], v9 offset1:2
	v_add_u32_e32 v9, v9, v59
	v_and_b32_e32 v9, 0x1fc, v9
	ds_read2st64_b32 v[134:135], v9 offset1:2
	v_add_u32_e32 v9, v9, v59
	v_and_b32_e32 v9, 0x1fc, v9
	ds_read2st64_b32 v[136:137], v9 offset1:2
	v_add_u32_e32 v9, v9, v59
	v_and_b32_e32 v9, 0x1fc, v9
	ds_read2st64_b32 v[138:139], v9 offset1:2
	v_add_u32_e32 v9, v9, v59
	v_and_b32_e32 v9, 0x1fc, v9
	s_waitcnt lgkmcnt(8)
	s_waitcnt vmcnt(32)
	v_fmac_f32_e32 v6, v92, v109
	v_fmac_f32_e32 v7, v92, v108
	v_fmac_f32_e32 v6, v93, v111
	v_fmac_f32_e32 v7, v93, v110
	v_fmac_f32_e32 v6, v94, v113
	v_fmac_f32_e32 v7, v94, v112
	v_fmac_f32_e32 v6, v95, v115
	v_fmac_f32_e32 v7, v95, v114
	v_fmac_f32_e32 v6, v96, v117
	v_fmac_f32_e32 v7, v96, v116
	v_fmac_f32_e32 v6, v97, v119
	v_fmac_f32_e32 v7, v97, v118
	v_fmac_f32_e32 v6, v98, v121
	v_fmac_f32_e32 v7, v98, v120
	v_fmac_f32_e32 v6, v99, v123
	v_fmac_f32_e32 v7, v99, v122
	ds_read2st64_b32 v[108:109], v9 offset1:2
	v_add_u32_e32 v9, v9, v59
	v_and_b32_e32 v9, 0x1fc, v9
	ds_read2st64_b32 v[110:111], v9 offset1:2
	v_add_u32_e32 v9, v9, v59
	v_and_b32_e32 v9, 0x1fc, v9
	ds_read2st64_b32 v[112:113], v9 offset1:2
	v_add_u32_e32 v9, v9, v59
	v_and_b32_e32 v9, 0x1fc, v9
	ds_read2st64_b32 v[114:115], v9 offset1:2
	v_add_u32_e32 v9, v9, v59
	v_and_b32_e32 v9, 0x1fc, v9
	ds_read2st64_b32 v[116:117], v9 offset1:2
	v_add_u32_e32 v9, v9, v59
	v_and_b32_e32 v9, 0x1fc, v9
	ds_read2st64_b32 v[118:119], v9 offset1:2
	v_add_u32_e32 v9, v9, v59
	v_and_b32_e32 v9, 0x1fc, v9
	ds_read2st64_b32 v[120:121], v9 offset1:2
	v_add_u32_e32 v9, v9, v59
	v_and_b32_e32 v9, 0x1fc, v9
	ds_read2st64_b32 v[122:123], v9 offset1:2
	v_add_u32_e32 v9, v9, v59
	v_and_b32_e32 v9, 0x1fc, v9
	s_waitcnt lgkmcnt(8)
	v_fmac_f32_e32 v6, v100, v125
	v_fmac_f32_e32 v7, v100, v124
	v_fmac_f32_e32 v6, v101, v127
	v_fmac_f32_e32 v7, v101, v126
	v_fmac_f32_e32 v6, v102, v129
	v_fmac_f32_e32 v7, v102, v128
	v_fmac_f32_e32 v6, v103, v131
	v_fmac_f32_e32 v7, v103, v130
	v_fmac_f32_e32 v6, v104, v133
	v_fmac_f32_e32 v7, v104, v132
	v_fmac_f32_e32 v6, v105, v135
	v_fmac_f32_e32 v7, v105, v134
	v_fmac_f32_e32 v6, v106, v137
	v_fmac_f32_e32 v7, v106, v136
	v_fmac_f32_e32 v6, v107, v139
	v_fmac_f32_e32 v7, v107, v138
	global_load_dword v92, v[10:11], off offset:-512
	global_load_dword v93, v[10:11], off
	global_load_dword v94, v[10:11], off offset:512
	global_load_dword v95, v[10:11], off offset:1024
	global_load_dword v96, v[10:11], off offset:1536
	global_load_dword v97, v[10:11], off offset:2048
	global_load_dword v98, v[10:11], off offset:2560
	global_load_dword v99, v[10:11], off offset:3072
	v_lshl_add_u64 v[10:11], v[10:11], 0, s[12:13]
	global_load_dword v100, v[10:11], off offset:-512
	global_load_dword v101, v[10:11], off
	global_load_dword v102, v[10:11], off offset:512
	global_load_dword v103, v[10:11], off offset:1024
	global_load_dword v104, v[10:11], off offset:1536
	global_load_dword v105, v[10:11], off offset:2048
	global_load_dword v106, v[10:11], off offset:2560
	global_load_dword v107, v[10:11], off offset:3072
	v_lshl_add_u64 v[10:11], v[10:11], 0, s[12:13]
	ds_read2st64_b32 v[124:125], v9 offset1:2
	v_add_u32_e32 v9, v9, v59
	v_and_b32_e32 v9, 0x1fc, v9
	ds_read2st64_b32 v[126:127], v9 offset1:2
	v_add_u32_e32 v9, v9, v59
	v_and_b32_e32 v9, 0x1fc, v9
	ds_read2st64_b32 v[128:129], v9 offset1:2
	v_add_u32_e32 v9, v9, v59
	v_and_b32_e32 v9, 0x1fc, v9
	ds_read2st64_b32 v[130:131], v9 offset1:2
	v_add_u32_e32 v9, v9, v59
	v_and_b32_e32 v9, 0x1fc, v9
	ds_read2st64_b32 v[132:133], v9 offset1:2
	v_add_u32_e32 v9, v9, v59
	v_and_b32_e32 v9, 0x1fc, v9
	ds_read2st64_b32 v[134:135], v9 offset1:2
	v_add_u32_e32 v9, v9, v59
	v_and_b32_e32 v9, 0x1fc, v9
	ds_read2st64_b32 v[136:137], v9 offset1:2
	v_add_u32_e32 v9, v9, v59
	v_and_b32_e32 v9, 0x1fc, v9
	ds_read2st64_b32 v[138:139], v9 offset1:2
	v_add_u32_e32 v9, v9, v59
	v_and_b32_e32 v9, 0x1fc, v9
	s_waitcnt lgkmcnt(8)
	s_waitcnt vmcnt(32)
	v_fmac_f32_e32 v6, v60, v109
	v_fmac_f32_e32 v7, v60, v108
	v_fmac_f32_e32 v6, v61, v111
	v_fmac_f32_e32 v7, v61, v110
	v_fmac_f32_e32 v6, v62, v113
	v_fmac_f32_e32 v7, v62, v112
	v_fmac_f32_e32 v6, v63, v115
	v_fmac_f32_e32 v7, v63, v114
	v_fmac_f32_e32 v6, v64, v117
	v_fmac_f32_e32 v7, v64, v116
	v_fmac_f32_e32 v6, v65, v119
	v_fmac_f32_e32 v7, v65, v118
	v_fmac_f32_e32 v6, v66, v121
	v_fmac_f32_e32 v7, v66, v120
	v_fmac_f32_e32 v6, v67, v123
	v_fmac_f32_e32 v7, v67, v122
	ds_read2st64_b32 v[108:109], v9 offset1:2
	v_add_u32_e32 v9, v9, v59
	v_and_b32_e32 v9, 0x1fc, v9
	ds_read2st64_b32 v[110:111], v9 offset1:2
	v_add_u32_e32 v9, v9, v59
	v_and_b32_e32 v9, 0x1fc, v9
	ds_read2st64_b32 v[112:113], v9 offset1:2
	v_add_u32_e32 v9, v9, v59
	v_and_b32_e32 v9, 0x1fc, v9
	ds_read2st64_b32 v[114:115], v9 offset1:2
	v_add_u32_e32 v9, v9, v59
	v_and_b32_e32 v9, 0x1fc, v9
	ds_read2st64_b32 v[116:117], v9 offset1:2
	v_add_u32_e32 v9, v9, v59
	v_and_b32_e32 v9, 0x1fc, v9
	ds_read2st64_b32 v[118:119], v9 offset1:2
	v_add_u32_e32 v9, v9, v59
	v_and_b32_e32 v9, 0x1fc, v9
	ds_read2st64_b32 v[120:121], v9 offset1:2
	v_add_u32_e32 v9, v9, v59
	v_and_b32_e32 v9, 0x1fc, v9
	ds_read2st64_b32 v[122:123], v9 offset1:2
	v_add_u32_e32 v9, v9, v59
	v_and_b32_e32 v9, 0x1fc, v9
	s_waitcnt lgkmcnt(8)
	v_fmac_f32_e32 v6, v68, v125
	v_fmac_f32_e32 v7, v68, v124
	v_fmac_f32_e32 v6, v69, v127
	v_fmac_f32_e32 v7, v69, v126
	v_fmac_f32_e32 v6, v70, v129
	v_fmac_f32_e32 v7, v70, v128
	v_fmac_f32_e32 v6, v71, v131
	v_fmac_f32_e32 v7, v71, v130
	v_fmac_f32_e32 v6, v72, v133
	v_fmac_f32_e32 v7, v72, v132
	v_fmac_f32_e32 v6, v73, v135
	v_fmac_f32_e32 v7, v73, v134
	v_fmac_f32_e32 v6, v74, v137
	v_fmac_f32_e32 v7, v74, v136
	v_fmac_f32_e32 v6, v75, v139
	v_fmac_f32_e32 v7, v75, v138
	global_load_dword v60, v[10:11], off offset:-512
	global_load_dword v61, v[10:11], off
	global_load_dword v62, v[10:11], off offset:512
	global_load_dword v63, v[10:11], off offset:1024
	global_load_dword v64, v[10:11], off offset:1536
	global_load_dword v65, v[10:11], off offset:2048
	global_load_dword v66, v[10:11], off offset:2560
	global_load_dword v67, v[10:11], off offset:3072
	v_lshl_add_u64 v[10:11], v[10:11], 0, s[12:13]
	global_load_dword v68, v[10:11], off offset:-512
	global_load_dword v69, v[10:11], off
	global_load_dword v70, v[10:11], off offset:512
	global_load_dword v71, v[10:11], off offset:1024
	global_load_dword v72, v[10:11], off offset:1536
	global_load_dword v73, v[10:11], off offset:2048
	global_load_dword v74, v[10:11], off offset:2560
	global_load_dword v75, v[10:11], off offset:3072
	v_lshl_add_u64 v[10:11], v[10:11], 0, s[12:13]
	ds_read2st64_b32 v[124:125], v9 offset1:2
	v_add_u32_e32 v9, v9, v59
	v_and_b32_e32 v9, 0x1fc, v9
	ds_read2st64_b32 v[126:127], v9 offset1:2
	v_add_u32_e32 v9, v9, v59
	v_and_b32_e32 v9, 0x1fc, v9
	ds_read2st64_b32 v[128:129], v9 offset1:2
	v_add_u32_e32 v9, v9, v59
	v_and_b32_e32 v9, 0x1fc, v9
	ds_read2st64_b32 v[130:131], v9 offset1:2
	v_add_u32_e32 v9, v9, v59
	v_and_b32_e32 v9, 0x1fc, v9
	ds_read2st64_b32 v[132:133], v9 offset1:2
	v_add_u32_e32 v9, v9, v59
	v_and_b32_e32 v9, 0x1fc, v9
	ds_read2st64_b32 v[134:135], v9 offset1:2
	v_add_u32_e32 v9, v9, v59
	v_and_b32_e32 v9, 0x1fc, v9
	ds_read2st64_b32 v[136:137], v9 offset1:2
	v_add_u32_e32 v9, v9, v59
	v_and_b32_e32 v9, 0x1fc, v9
	ds_read2st64_b32 v[138:139], v9 offset1:2
	v_add_u32_e32 v9, v9, v59
	v_and_b32_e32 v9, 0x1fc, v9
	s_waitcnt lgkmcnt(8)
	s_waitcnt vmcnt(32)
	v_fmac_f32_e32 v6, v76, v109
	v_fmac_f32_e32 v7, v76, v108
	v_fmac_f32_e32 v6, v77, v111
	v_fmac_f32_e32 v7, v77, v110
	v_fmac_f32_e32 v6, v78, v113
	v_fmac_f32_e32 v7, v78, v112
	v_fmac_f32_e32 v6, v79, v115
	v_fmac_f32_e32 v7, v79, v114
	v_fmac_f32_e32 v6, v80, v117
	v_fmac_f32_e32 v7, v80, v116
	v_fmac_f32_e32 v6, v81, v119
	v_fmac_f32_e32 v7, v81, v118
	v_fmac_f32_e32 v6, v82, v121
	v_fmac_f32_e32 v7, v82, v120
	v_fmac_f32_e32 v6, v83, v123
	v_fmac_f32_e32 v7, v83, v122
	ds_read2st64_b32 v[108:109], v9 offset1:2
	v_add_u32_e32 v9, v9, v59
	v_and_b32_e32 v9, 0x1fc, v9
	ds_read2st64_b32 v[110:111], v9 offset1:2
	v_add_u32_e32 v9, v9, v59
	v_and_b32_e32 v9, 0x1fc, v9
	ds_read2st64_b32 v[112:113], v9 offset1:2
	v_add_u32_e32 v9, v9, v59
	v_and_b32_e32 v9, 0x1fc, v9
	ds_read2st64_b32 v[114:115], v9 offset1:2
	v_add_u32_e32 v9, v9, v59
	v_and_b32_e32 v9, 0x1fc, v9
	ds_read2st64_b32 v[116:117], v9 offset1:2
	v_add_u32_e32 v9, v9, v59
	v_and_b32_e32 v9, 0x1fc, v9
	ds_read2st64_b32 v[118:119], v9 offset1:2
	v_add_u32_e32 v9, v9, v59
	v_and_b32_e32 v9, 0x1fc, v9
	ds_read2st64_b32 v[120:121], v9 offset1:2
	v_add_u32_e32 v9, v9, v59
	v_and_b32_e32 v9, 0x1fc, v9
	ds_read2st64_b32 v[122:123], v9 offset1:2
	v_add_u32_e32 v9, v9, v59
	v_and_b32_e32 v9, 0x1fc, v9
	s_waitcnt lgkmcnt(8)
	v_fmac_f32_e32 v6, v84, v125
	v_fmac_f32_e32 v7, v84, v124
	v_fmac_f32_e32 v6, v85, v127
	v_fmac_f32_e32 v7, v85, v126
	v_fmac_f32_e32 v6, v86, v129
	v_fmac_f32_e32 v7, v86, v128
	v_fmac_f32_e32 v6, v87, v131
	v_fmac_f32_e32 v7, v87, v130
	v_fmac_f32_e32 v6, v88, v133
	v_fmac_f32_e32 v7, v88, v132
	v_fmac_f32_e32 v6, v89, v135
	v_fmac_f32_e32 v7, v89, v134
	v_fmac_f32_e32 v6, v90, v137
	v_fmac_f32_e32 v7, v90, v136
	v_fmac_f32_e32 v6, v91, v139
	v_fmac_f32_e32 v7, v91, v138
	global_load_dword v76, v[10:11], off offset:-512
	global_load_dword v77, v[10:11], off
	global_load_dword v78, v[10:11], off offset:512
	global_load_dword v79, v[10:11], off offset:1024
	global_load_dword v80, v[10:11], off offset:1536
	global_load_dword v81, v[10:11], off offset:2048
	global_load_dword v82, v[10:11], off offset:2560
	global_load_dword v83, v[10:11], off offset:3072
	v_lshl_add_u64 v[10:11], v[10:11], 0, s[12:13]
	global_load_dword v84, v[10:11], off offset:-512
	global_load_dword v85, v[10:11], off
	global_load_dword v86, v[10:11], off offset:512
	global_load_dword v87, v[10:11], off offset:1024
	global_load_dword v88, v[10:11], off offset:1536
	global_load_dword v89, v[10:11], off offset:2048
	global_load_dword v90, v[10:11], off offset:2560
	global_load_dword v91, v[10:11], off offset:3072
	v_lshl_add_u64 v[10:11], v[10:11], 0, s[12:13]
	ds_read2st64_b32 v[124:125], v9 offset1:2
	v_add_u32_e32 v9, v9, v59
	v_and_b32_e32 v9, 0x1fc, v9
	ds_read2st64_b32 v[126:127], v9 offset1:2
	v_add_u32_e32 v9, v9, v59
	v_and_b32_e32 v9, 0x1fc, v9
	ds_read2st64_b32 v[128:129], v9 offset1:2
	v_add_u32_e32 v9, v9, v59
	v_and_b32_e32 v9, 0x1fc, v9
	ds_read2st64_b32 v[130:131], v9 offset1:2
	v_add_u32_e32 v9, v9, v59
	v_and_b32_e32 v9, 0x1fc, v9
	ds_read2st64_b32 v[132:133], v9 offset1:2
	v_add_u32_e32 v9, v9, v59
	v_and_b32_e32 v9, 0x1fc, v9
	ds_read2st64_b32 v[134:135], v9 offset1:2
	v_add_u32_e32 v9, v9, v59
	v_and_b32_e32 v9, 0x1fc, v9
	ds_read2st64_b32 v[136:137], v9 offset1:2
	v_add_u32_e32 v9, v9, v59
	v_and_b32_e32 v9, 0x1fc, v9
	ds_read2st64_b32 v[138:139], v9 offset1:2
	v_add_u32_e32 v9, v9, v59
	v_and_b32_e32 v9, 0x1fc, v9
	s_waitcnt lgkmcnt(8)
	s_waitcnt vmcnt(32)
	v_fmac_f32_e32 v6, v92, v109
	v_fmac_f32_e32 v7, v92, v108
	v_fmac_f32_e32 v6, v93, v111
	v_fmac_f32_e32 v7, v93, v110
	v_fmac_f32_e32 v6, v94, v113
	v_fmac_f32_e32 v7, v94, v112
	v_fmac_f32_e32 v6, v95, v115
	v_fmac_f32_e32 v7, v95, v114
	v_fmac_f32_e32 v6, v96, v117
	v_fmac_f32_e32 v7, v96, v116
	v_fmac_f32_e32 v6, v97, v119
	v_fmac_f32_e32 v7, v97, v118
	v_fmac_f32_e32 v6, v98, v121
	v_fmac_f32_e32 v7, v98, v120
	v_fmac_f32_e32 v6, v99, v123
	v_fmac_f32_e32 v7, v99, v122
	ds_read2st64_b32 v[108:109], v9 offset1:2
	v_add_u32_e32 v9, v9, v59
	v_and_b32_e32 v9, 0x1fc, v9
	ds_read2st64_b32 v[110:111], v9 offset1:2
	v_add_u32_e32 v9, v9, v59
	v_and_b32_e32 v9, 0x1fc, v9
	ds_read2st64_b32 v[112:113], v9 offset1:2
	v_add_u32_e32 v9, v9, v59
	v_and_b32_e32 v9, 0x1fc, v9
	ds_read2st64_b32 v[114:115], v9 offset1:2
	v_add_u32_e32 v9, v9, v59
	v_and_b32_e32 v9, 0x1fc, v9
	ds_read2st64_b32 v[116:117], v9 offset1:2
	v_add_u32_e32 v9, v9, v59
	v_and_b32_e32 v9, 0x1fc, v9
	ds_read2st64_b32 v[118:119], v9 offset1:2
	v_add_u32_e32 v9, v9, v59
	v_and_b32_e32 v9, 0x1fc, v9
	ds_read2st64_b32 v[120:121], v9 offset1:2
	v_add_u32_e32 v9, v9, v59
	v_and_b32_e32 v9, 0x1fc, v9
	ds_read2st64_b32 v[122:123], v9 offset1:2
	v_add_u32_e32 v9, v9, v59
	v_and_b32_e32 v9, 0x1fc, v9
	s_waitcnt lgkmcnt(8)
	v_fmac_f32_e32 v6, v100, v125
	v_fmac_f32_e32 v7, v100, v124
	v_fmac_f32_e32 v6, v101, v127
	v_fmac_f32_e32 v7, v101, v126
	v_fmac_f32_e32 v6, v102, v129
	v_fmac_f32_e32 v7, v102, v128
	v_fmac_f32_e32 v6, v103, v131
	v_fmac_f32_e32 v7, v103, v130
	v_fmac_f32_e32 v6, v104, v133
	v_fmac_f32_e32 v7, v104, v132
	v_fmac_f32_e32 v6, v105, v135
	v_fmac_f32_e32 v7, v105, v134
	v_fmac_f32_e32 v6, v106, v137
	v_fmac_f32_e32 v7, v106, v136
	v_fmac_f32_e32 v6, v107, v139
	v_fmac_f32_e32 v7, v107, v138
	ds_read2st64_b32 v[124:125], v9 offset1:2
	v_add_u32_e32 v9, v9, v59
	v_and_b32_e32 v9, 0x1fc, v9
	ds_read2st64_b32 v[126:127], v9 offset1:2
	v_add_u32_e32 v9, v9, v59
	v_and_b32_e32 v9, 0x1fc, v9
	ds_read2st64_b32 v[128:129], v9 offset1:2
	v_add_u32_e32 v9, v9, v59
	v_and_b32_e32 v9, 0x1fc, v9
	ds_read2st64_b32 v[130:131], v9 offset1:2
	v_add_u32_e32 v9, v9, v59
	v_and_b32_e32 v9, 0x1fc, v9
	ds_read2st64_b32 v[132:133], v9 offset1:2
	v_add_u32_e32 v9, v9, v59
	v_and_b32_e32 v9, 0x1fc, v9
	ds_read2st64_b32 v[134:135], v9 offset1:2
	v_add_u32_e32 v9, v9, v59
	v_and_b32_e32 v9, 0x1fc, v9
	ds_read2st64_b32 v[136:137], v9 offset1:2
	v_add_u32_e32 v9, v9, v59
	v_and_b32_e32 v9, 0x1fc, v9
	ds_read2st64_b32 v[138:139], v9 offset1:2
	v_add_u32_e32 v9, v9, v59
	v_and_b32_e32 v9, 0x1fc, v9
	s_waitcnt lgkmcnt(8)
	s_waitcnt vmcnt(16)
	v_fmac_f32_e32 v6, v60, v109
	v_fmac_f32_e32 v7, v60, v108
	v_fmac_f32_e32 v6, v61, v111
	v_fmac_f32_e32 v7, v61, v110
	v_fmac_f32_e32 v6, v62, v113
	v_fmac_f32_e32 v7, v62, v112
	v_fmac_f32_e32 v6, v63, v115
	v_fmac_f32_e32 v7, v63, v114
	v_fmac_f32_e32 v6, v64, v117
	v_fmac_f32_e32 v7, v64, v116
	v_fmac_f32_e32 v6, v65, v119
	v_fmac_f32_e32 v7, v65, v118
	v_fmac_f32_e32 v6, v66, v121
	v_fmac_f32_e32 v7, v66, v120
	v_fmac_f32_e32 v6, v67, v123
	v_fmac_f32_e32 v7, v67, v122
	ds_read2st64_b32 v[108:109], v9 offset1:2
	v_add_u32_e32 v9, v9, v59
	v_and_b32_e32 v9, 0x1fc, v9
	ds_read2st64_b32 v[110:111], v9 offset1:2
	v_add_u32_e32 v9, v9, v59
	v_and_b32_e32 v9, 0x1fc, v9
	ds_read2st64_b32 v[112:113], v9 offset1:2
	v_add_u32_e32 v9, v9, v59
	v_and_b32_e32 v9, 0x1fc, v9
	ds_read2st64_b32 v[114:115], v9 offset1:2
	v_add_u32_e32 v9, v9, v59
	v_and_b32_e32 v9, 0x1fc, v9
	ds_read2st64_b32 v[116:117], v9 offset1:2
	v_add_u32_e32 v9, v9, v59
	v_and_b32_e32 v9, 0x1fc, v9
	ds_read2st64_b32 v[118:119], v9 offset1:2
	v_add_u32_e32 v9, v9, v59
	v_and_b32_e32 v9, 0x1fc, v9
	ds_read2st64_b32 v[120:121], v9 offset1:2
	v_add_u32_e32 v9, v9, v59
	v_and_b32_e32 v9, 0x1fc, v9
	ds_read2st64_b32 v[122:123], v9 offset1:2
	v_add_u32_e32 v9, v9, v59
	v_and_b32_e32 v9, 0x1fc, v9
	s_waitcnt lgkmcnt(8)
	v_fmac_f32_e32 v6, v68, v125
	v_fmac_f32_e32 v7, v68, v124
	v_fmac_f32_e32 v6, v69, v127
	v_fmac_f32_e32 v7, v69, v126
	v_fmac_f32_e32 v6, v70, v129
	v_fmac_f32_e32 v7, v70, v128
	v_fmac_f32_e32 v6, v71, v131
	v_fmac_f32_e32 v7, v71, v130
	v_fmac_f32_e32 v6, v72, v133
	v_fmac_f32_e32 v7, v72, v132
	v_fmac_f32_e32 v6, v73, v135
	v_fmac_f32_e32 v7, v73, v134
	v_fmac_f32_e32 v6, v74, v137
	v_fmac_f32_e32 v7, v74, v136
	v_fmac_f32_e32 v6, v75, v139
	v_fmac_f32_e32 v7, v75, v138
	ds_read2st64_b32 v[124:125], v9 offset1:2
	v_add_u32_e32 v9, v9, v59
	v_and_b32_e32 v9, 0x1fc, v9
	ds_read2st64_b32 v[126:127], v9 offset1:2
	v_add_u32_e32 v9, v9, v59
	v_and_b32_e32 v9, 0x1fc, v9
	ds_read2st64_b32 v[128:129], v9 offset1:2
	v_add_u32_e32 v9, v9, v59
	v_and_b32_e32 v9, 0x1fc, v9
	ds_read2st64_b32 v[130:131], v9 offset1:2
	v_add_u32_e32 v9, v9, v59
	v_and_b32_e32 v9, 0x1fc, v9
	ds_read2st64_b32 v[132:133], v9 offset1:2
	v_add_u32_e32 v9, v9, v59
	v_and_b32_e32 v9, 0x1fc, v9
	ds_read2st64_b32 v[134:135], v9 offset1:2
	v_add_u32_e32 v9, v9, v59
	v_and_b32_e32 v9, 0x1fc, v9
	ds_read2st64_b32 v[136:137], v9 offset1:2
	v_add_u32_e32 v9, v9, v59
	v_and_b32_e32 v9, 0x1fc, v9
	ds_read2st64_b32 v[138:139], v9 offset1:2
	v_add_u32_e32 v9, v9, v59
	v_and_b32_e32 v9, 0x1fc, v9
	s_waitcnt lgkmcnt(8)
	s_waitcnt vmcnt(0)
	v_fmac_f32_e32 v6, v76, v109
	v_fmac_f32_e32 v7, v76, v108
	v_fmac_f32_e32 v6, v77, v111
	v_fmac_f32_e32 v7, v77, v110
	v_fmac_f32_e32 v6, v78, v113
	v_fmac_f32_e32 v7, v78, v112
	v_fmac_f32_e32 v6, v79, v115
	v_fmac_f32_e32 v7, v79, v114
	v_fmac_f32_e32 v6, v80, v117
	v_fmac_f32_e32 v7, v80, v116
	v_fmac_f32_e32 v6, v81, v119
	v_fmac_f32_e32 v7, v81, v118
	v_fmac_f32_e32 v6, v82, v121
	v_fmac_f32_e32 v7, v82, v120
	v_fmac_f32_e32 v6, v83, v123
	v_fmac_f32_e32 v7, v83, v122
	s_waitcnt lgkmcnt(0)
	v_fmac_f32_e32 v6, v84, v125
	v_fmac_f32_e32 v7, v84, v124
	v_fmac_f32_e32 v6, v85, v127
	v_fmac_f32_e32 v7, v85, v126
	v_fmac_f32_e32 v6, v86, v129
	v_fmac_f32_e32 v7, v86, v128
	v_fmac_f32_e32 v6, v87, v131
	v_fmac_f32_e32 v7, v87, v130
	v_fmac_f32_e32 v6, v88, v133
	v_fmac_f32_e32 v7, v88, v132
	v_fmac_f32_e32 v6, v89, v135
	v_fmac_f32_e32 v7, v89, v134
	v_fmac_f32_e32 v6, v90, v137
	v_fmac_f32_e32 v7, v90, v136
	v_fmac_f32_e32 v6, v91, v139
	v_fmac_f32_e32 v7, v91, v138
	v_ashrrev_i32_e32 v5, 31, v4
	v_lshlrev_b64 v[8:9], 2, v[4:5]
	v_add_u32_e32 v4, s4, v4
	v_cmp_lt_i32_e32 vcc, s5, v4
	v_lshl_add_u64 v[10:11], s[70:71], 0, v[8:9]
	v_lshl_add_u64 v[8:9], s[68:69], 0, v[8:9]
	s_or_b64 s[10:11], vcc, s[10:11]
	global_store_dword v[10:11], v7, off
	global_store_dword v[8:9], v6, off
	s_andn2_b64 exec, exec, s[10:11]
	s_cbranch_execnz .LBB0_71
